# P4 SwiGLU epilogue: next-unit rstd prefetched during epilogue, no load waits between blocks
# speedup vs baseline: 1.0111x; 1.0111x over previous
.LBB0_787:
	s_add_u32 s8, s84, 0x1e00000
	s_addc_u32 s9, s85, 0
	s_add_u32 s10, s84, 0x14d00000
	s_mov_b64 s[12:13], 0x80
	s_addc_u32 s11, s85, 0
	s_and_b32 s16, s0, 0x60
	s_add_i32 m0, s35, 0x18000
	v_lshl_add_u64 v[6:7], v[6:7], 0, s[12:13]
	s_lshl_b32 s4, s3, 13
	s_lshr_b32 s17, s16, 3
	s_waitcnt vmcnt(2)
	s_barrier
	global_load_lds_dwordx4 v[6:7], off
	v_lshl_add_u64 v[4:5], v[4:5], 0, s[12:13]
	s_add_i32 m0, s35, 0x1a000
	s_add_i32 s43, s35, 0x8000
	s_add_i32 s44, s35, 0xa000
	global_load_lds_dwordx4 v[4:5], off
	v_lshl_add_u64 v[0:1], v[0:1], 0, s[12:13]
	s_mov_b32 m0, s43
	s_add_u32 s14, s38, 0x40080
	global_load_lds_dwordx4 v[0:1], off
	v_lshl_add_u64 v[0:1], v[2:3], 0, s[12:13]
	s_mov_b32 m0, s44
	s_addc_u32 s15, s39, 0
	global_load_lds_dwordx4 v[0:1], off
	s_add_i32 m0, s35, 0x1c000
	v_lshl_add_u64 v[0:1], s[14:15], 0, v[132:133]
	global_load_lds_dwordx4 v[0:1], off
	v_lshl_add_u64 v[0:1], s[14:15], 0, v[128:129]
	s_add_i32 m0, s35, 0x1e000
	v_and_b32_e32 v3, 48, v10
	global_load_lds_dwordx4 v[0:1], off
	v_and_b32_e32 v1, 15, v10
	v_lshl_or_b32 v150, s3, 6, v1
	v_ashrrev_i32_e32 v2, 6, v10
	v_lshl_or_b32 v1, v1, 6, v3
	v_lshlrev_b32_e32 v3, 2, v10
	v_lshl_add_u32 v4, v2, 10, s4
	v_and_b32_e32 v3, 32, v3
	v_add_lshl_u32 v2, v2, s17, 10
	v_bitop3_b32 v151, v1, v2, v3 bitop3:0xde
	v_lshlrev_b32_e32 v2, 14, v12
	v_and_b32_e32 v2, 0xffff8000, v2
	v_bitop3_b32 v4, v1, v4, v3 bitop3:0xde
	v_lshl_add_u32 v2, v13, 11, v2
	v_and_b32_e32 v3, 1, v12
	v_lshl_or_b32 v2, v3, 6, v2
	v_lshl_add_u32 v136, v14, 1, v2
	v_lshlrev_b32_e32 v2, 14, v8
	v_ashrrev_i32_e32 v0, 1, v10
	v_and_b32_e32 v2, 0xffff8000, v2
	v_and_b32_e32 v0, -8, v0
	s_waitcnt vmcnt(6)
	s_cmpk_lt_u32 s82, 0x100
	v_lshl_add_u32 v2, v9, 11, v2
	v_and_b32_e32 v3, 1, v8
	s_cselect_b64 s[14:15], -1, 0
	v_ashrrev_i32_e32 v1, 31, v0
	v_lshl_or_b32 v2, v3, 6, v2
	s_add_i32 s46, 0, 0x10000
	s_add_i32 s47, 0, 0x14000
	s_sext_i32_i16 s31, s2
	s_ashr_i32 s45, s67, 31
	v_mov_b32_e32 v137, v133
	v_lshl_add_u32 v138, v11, 1, v2
	v_mov_b32_e32 v139, v133
	v_mov_b64_e32 v[140:141], 0x1658
	v_mov_b64_e32 v[142:143], 0x1657
	v_add_u32_e32 v152, s46, v151
	v_add_u32_e32 v153, s47, v151
	v_add_u32_e32 v154, 0, v4
	v_mov_b32_e32 v155, 0x358637bd
	s_mov_b32 s48, 0x800000
	s_movk_i32 s49, 0x1600
	s_lshl_b32 s4, s16, 1
	v_lshlrev_b64 v[144:145], 1, v[0:1]
	s_mov_b32 s50, s5
	s_barrier
	v_lshl_add_u32 v148, s30, 8, v150
	v_mov_b32_e32 v149, 0
	v_lshlrev_b64 v[148:149], 6, v[148:149]
	v_lshl_add_u64 v[148:149], s[8:9], 0, v[148:149]
	v_lshl_add_u64 v[148:149], v[148:149], 0, v[144:145]
	s_mov_b64 s[40:41], 0x2000
	global_load_dwordx4 v[156:159], v[148:149], off
	global_load_dwordx4 v[160:163], v[148:149], off offset:1024
	global_load_dwordx4 v[164:167], v[148:149], off offset:2048
	global_load_dwordx4 v[168:171], v[148:149], off offset:3072
	v_lshl_add_u64 v[148:149], v[148:149], 0, s[40:41]
	global_load_dwordx4 v[172:175], v[148:149], off
	global_load_dwordx4 v[176:179], v[148:149], off offset:1024
	global_load_dwordx4 v[180:183], v[148:149], off offset:2048
	global_load_dwordx4 v[184:187], v[148:149], off offset:3072
	s_waitcnt vmcnt(0)
	v_add_f32_e32 v156, v156, v157
	v_add_f32_e32 v160, v160, v161
	v_add_f32_e32 v164, v164, v165
	v_add_f32_e32 v168, v168, v169
	v_add_f32_e32 v172, v172, v173
	v_add_f32_e32 v176, v176, v177
	v_add_f32_e32 v180, v180, v181
	v_add_f32_e32 v184, v184, v185
	v_add_f32_e32 v158, v158, v159
	v_add_f32_e32 v162, v162, v163
	v_add_f32_e32 v166, v166, v167
	v_add_f32_e32 v170, v170, v171
	v_add_f32_e32 v174, v174, v175
	v_add_f32_e32 v178, v178, v179
	v_add_f32_e32 v182, v182, v183
	v_add_f32_e32 v186, v186, v187
	v_add_f32_e32 v156, v156, v158
	v_add_f32_e32 v160, v160, v162
	v_add_f32_e32 v164, v164, v166
	v_add_f32_e32 v168, v168, v170
	v_add_f32_e32 v172, v172, v174
	v_add_f32_e32 v176, v176, v178
	v_add_f32_e32 v180, v180, v182
	v_add_f32_e32 v184, v184, v186
	v_mov_b32_e32 v157, v156
	v_mov_b32_e32 v161, v160
	v_mov_b32_e32 v165, v164
	v_mov_b32_e32 v169, v168
	v_mov_b32_e32 v173, v172
	v_mov_b32_e32 v177, v176
	v_mov_b32_e32 v181, v180
	v_mov_b32_e32 v185, v184
	v_permlane16_swap_b32_e32 v157, v156
	v_permlane16_swap_b32_e32 v161, v160
	v_permlane16_swap_b32_e32 v165, v164
	v_permlane16_swap_b32_e32 v169, v168
	v_permlane16_swap_b32_e32 v173, v172
	v_permlane16_swap_b32_e32 v177, v176
	v_permlane16_swap_b32_e32 v181, v180
	v_permlane16_swap_b32_e32 v185, v184
	v_add_f32_e32 v156, v156, v157
	v_add_f32_e32 v160, v160, v161
	v_add_f32_e32 v164, v164, v165
	v_add_f32_e32 v168, v168, v169
	v_add_f32_e32 v172, v172, v173
	v_add_f32_e32 v176, v176, v177
	v_add_f32_e32 v180, v180, v181
	v_add_f32_e32 v184, v184, v185
	v_mov_b32_e32 v157, v156
	v_mov_b32_e32 v161, v160
	v_mov_b32_e32 v165, v164
	v_mov_b32_e32 v169, v168
	v_mov_b32_e32 v173, v172
	v_mov_b32_e32 v177, v176
	v_mov_b32_e32 v181, v180
	v_mov_b32_e32 v185, v184
	v_permlane32_swap_b32_e32 v157, v156
	v_permlane32_swap_b32_e32 v161, v160
	v_permlane32_swap_b32_e32 v165, v164
	v_permlane32_swap_b32_e32 v169, v168
	v_permlane32_swap_b32_e32 v173, v172
	v_permlane32_swap_b32_e32 v177, v176
	v_permlane32_swap_b32_e32 v181, v180
	v_permlane32_swap_b32_e32 v185, v184
	v_add_f32_e32 v156, v156, v157
	v_add_f32_e32 v160, v160, v161
	v_add_f32_e32 v164, v164, v165
	v_add_f32_e32 v168, v168, v169
	v_add_f32_e32 v172, v172, v173
	v_add_f32_e32 v176, v176, v177
	v_add_f32_e32 v180, v180, v181
	v_add_f32_e32 v184, v184, v185
	v_fmamk_f32 v156, v156, 0x3a800000, v155
	v_fmamk_f32 v160, v160, 0x3a800000, v155
	v_fmamk_f32 v164, v164, 0x3a800000, v155
	v_fmamk_f32 v168, v168, 0x3a800000, v155
	v_fmamk_f32 v172, v172, 0x3a800000, v155
	v_fmamk_f32 v176, v176, 0x3a800000, v155
	v_fmamk_f32 v180, v180, 0x3a800000, v155
	v_fmamk_f32 v184, v184, 0x3a800000, v155
	v_rsq_f32_e32 v226, v156
	v_rsq_f32_e32 v228, v160
	v_rsq_f32_e32 v230, v164
	v_rsq_f32_e32 v232, v168
	v_rsq_f32_e32 v234, v172
	v_rsq_f32_e32 v236, v176
	v_rsq_f32_e32 v238, v180
	v_rsq_f32_e32 v240, v184
	s_branch .LBB0_790

.LBB0_796:
	s_and_b64 vcc, exec, s[2:3]
	s_cbranch_vccz .Lp4_noload
	v_lshl_add_u32 v148, s18, 8, v150
	v_mov_b32_e32 v149, 0
	v_lshlrev_b64 v[148:149], 6, v[148:149]
	v_lshl_add_u64 v[148:149], s[8:9], 0, v[148:149]
	v_lshl_add_u64 v[148:149], v[148:149], 0, v[144:145]
	s_mov_b64 s[40:41], 0x2000
	global_load_dwordx4 v[156:159], v[148:149], off
	global_load_dwordx4 v[160:163], v[148:149], off offset:1024
	global_load_dwordx4 v[164:167], v[148:149], off offset:2048
	global_load_dwordx4 v[168:171], v[148:149], off offset:3072
	v_lshl_add_u64 v[148:149], v[148:149], 0, s[40:41]
	global_load_dwordx4 v[172:175], v[148:149], off
	global_load_dwordx4 v[176:179], v[148:149], off offset:1024
	global_load_dwordx4 v[180:183], v[148:149], off offset:2048
	global_load_dwordx4 v[184:187], v[148:149], off offset:3072
.Lp4_noload:
	v_lshl_add_u32 v188, s30, 8, v150
	v_mov_b64_e32 v[146:147], s[10:11]
	v_mad_i64_i32 v[146:147], s[40:41], v188, s49, v[146:147]
	s_lshl_b32 s20, s31, 8
	s_mov_b32 s21, 0
	s_mov_b64 s[52:53], 0x16000
	s_mov_b64 s[54:55], 0x6e000
	v_lshl_add_u64 v[146:147], v[146:147], 0, s[20:21]
	v_lshl_add_u64 v[146:147], v[146:147], 0, s[4:5]
	v_lshl_add_u64 v[146:147], v[146:147], 0, v[144:145]
	v_pk_mul_f32 v[124:125], v[124:125], v[226:227] op_sel_hi:[1,0]
	v_pk_mul_f32 v[116:117], v[116:117], v[226:227] op_sel_hi:[1,0]
	v_pk_mul_f32 v[126:127], v[126:127], v[226:227] op_sel_hi:[1,0]
	v_pk_mul_f32 v[118:119], v[118:119], v[226:227] op_sel_hi:[1,0]
	v_pk_mul_f32 v[120:121], v[120:121], v[226:227] op_sel_hi:[1,0]
	v_pk_mul_f32 v[112:113], v[112:113], v[226:227] op_sel_hi:[1,0]
	v_pk_mul_f32 v[122:123], v[122:123], v[226:227] op_sel_hi:[1,0]
	v_pk_mul_f32 v[114:115], v[114:115], v[226:227] op_sel_hi:[1,0]
	v_mul_f32_e32 v188, 0xbfb8aa3b, v124
	v_mul_f32_e32 v189, 0xbfb8aa3b, v125
	v_mul_f32_e32 v190, 0xbfb8aa3b, v126
	v_mul_f32_e32 v191, 0xbfb8aa3b, v127
	v_mul_f32_e32 v192, 0xbfb8aa3b, v120
	v_mul_f32_e32 v193, 0xbfb8aa3b, v121
	v_mul_f32_e32 v194, 0xbfb8aa3b, v122
	v_mul_f32_e32 v195, 0xbfb8aa3b, v123
	v_pk_mul_f32 v[116:117], v[124:125], v[116:117]
	v_pk_mul_f32 v[118:119], v[126:127], v[118:119]
	v_pk_mul_f32 v[112:113], v[120:121], v[112:113]
	v_pk_mul_f32 v[114:115], v[122:123], v[114:115]
	v_exp_f32_e32 v188, v188
	v_exp_f32_e32 v189, v189
	v_exp_f32_e32 v190, v190
	v_exp_f32_e32 v191, v191
	v_exp_f32_e32 v192, v192
	v_exp_f32_e32 v193, v193
	v_exp_f32_e32 v194, v194
	v_exp_f32_e32 v195, v195
	v_add_f32_e32 v188, 1.0, v188
	v_add_f32_e32 v189, 1.0, v189
	v_add_f32_e32 v190, 1.0, v190
	v_add_f32_e32 v191, 1.0, v191
	v_add_f32_e32 v192, 1.0, v192
	v_add_f32_e32 v193, 1.0, v193
	v_add_f32_e32 v194, 1.0, v194
	v_add_f32_e32 v195, 1.0, v195
	v_rcp_f32_e32 v124, v188
	v_rcp_f32_e32 v125, v189
	v_rcp_f32_e32 v126, v190
	v_rcp_f32_e32 v127, v191
	v_rcp_f32_e32 v120, v192
	v_rcp_f32_e32 v121, v193
	v_rcp_f32_e32 v122, v194
	v_rcp_f32_e32 v123, v195
	v_pk_mul_f32 v[116:117], v[116:117], v[124:125]
	v_pk_mul_f32 v[118:119], v[118:119], v[126:127]
	v_pk_mul_f32 v[112:113], v[112:113], v[120:121]
	v_pk_mul_f32 v[114:115], v[114:115], v[122:123]
	v_cvt_pk_bf16_f32 v124, v116, v117
	v_cvt_pk_bf16_f32 v125, v118, v119
	v_cvt_pk_bf16_f32 v126, v112, v113
	v_cvt_pk_bf16_f32 v127, v114, v115
	global_store_dwordx4 v[146:147], v[124:127], off
	v_lshl_add_u64 v[146:147], v[146:147], 0, s[52:53]
	v_pk_mul_f32 v[108:109], v[108:109], v[228:229] op_sel_hi:[1,0]
	v_pk_mul_f32 v[100:101], v[100:101], v[228:229] op_sel_hi:[1,0]
	v_pk_mul_f32 v[110:111], v[110:111], v[228:229] op_sel_hi:[1,0]
	v_pk_mul_f32 v[102:103], v[102:103], v[228:229] op_sel_hi:[1,0]
	v_pk_mul_f32 v[104:105], v[104:105], v[228:229] op_sel_hi:[1,0]
	v_pk_mul_f32 v[96:97], v[96:97], v[228:229] op_sel_hi:[1,0]
	v_pk_mul_f32 v[106:107], v[106:107], v[228:229] op_sel_hi:[1,0]
	v_pk_mul_f32 v[98:99], v[98:99], v[228:229] op_sel_hi:[1,0]
	v_mul_f32_e32 v188, 0xbfb8aa3b, v108
	v_mul_f32_e32 v189, 0xbfb8aa3b, v109
	v_mul_f32_e32 v190, 0xbfb8aa3b, v110
	v_mul_f32_e32 v191, 0xbfb8aa3b, v111
	v_mul_f32_e32 v192, 0xbfb8aa3b, v104
	v_mul_f32_e32 v193, 0xbfb8aa3b, v105
	v_mul_f32_e32 v194, 0xbfb8aa3b, v106
	v_mul_f32_e32 v195, 0xbfb8aa3b, v107
	v_pk_mul_f32 v[100:101], v[108:109], v[100:101]
	v_pk_mul_f32 v[102:103], v[110:111], v[102:103]
	v_pk_mul_f32 v[96:97], v[104:105], v[96:97]
	v_pk_mul_f32 v[98:99], v[106:107], v[98:99]
	v_exp_f32_e32 v188, v188
	v_exp_f32_e32 v189, v189
	v_exp_f32_e32 v190, v190
	v_exp_f32_e32 v191, v191
	v_exp_f32_e32 v192, v192
	v_exp_f32_e32 v193, v193
	v_exp_f32_e32 v194, v194
	v_exp_f32_e32 v195, v195
	v_add_f32_e32 v188, 1.0, v188
	v_add_f32_e32 v189, 1.0, v189
	v_add_f32_e32 v190, 1.0, v190
	v_add_f32_e32 v191, 1.0, v191
	v_add_f32_e32 v192, 1.0, v192
	v_add_f32_e32 v193, 1.0, v193
	v_add_f32_e32 v194, 1.0, v194
	v_add_f32_e32 v195, 1.0, v195
	v_rcp_f32_e32 v108, v188
	v_rcp_f32_e32 v109, v189
	v_rcp_f32_e32 v110, v190
	v_rcp_f32_e32 v111, v191
	v_rcp_f32_e32 v104, v192
	v_rcp_f32_e32 v105, v193
	v_rcp_f32_e32 v106, v194
	v_rcp_f32_e32 v107, v195
	v_pk_mul_f32 v[100:101], v[100:101], v[108:109]
	v_pk_mul_f32 v[102:103], v[102:103], v[110:111]
	v_pk_mul_f32 v[96:97], v[96:97], v[104:105]
	v_pk_mul_f32 v[98:99], v[98:99], v[106:107]
	v_cvt_pk_bf16_f32 v108, v100, v101
	v_cvt_pk_bf16_f32 v109, v102, v103
	v_cvt_pk_bf16_f32 v110, v96, v97
	v_cvt_pk_bf16_f32 v111, v98, v99
	global_store_dwordx4 v[146:147], v[108:111], off
	v_lshl_add_u64 v[146:147], v[146:147], 0, s[52:53]
	v_pk_mul_f32 v[92:93], v[92:93], v[230:231] op_sel_hi:[1,0]
	v_pk_mul_f32 v[84:85], v[84:85], v[230:231] op_sel_hi:[1,0]
	v_pk_mul_f32 v[94:95], v[94:95], v[230:231] op_sel_hi:[1,0]
	v_pk_mul_f32 v[86:87], v[86:87], v[230:231] op_sel_hi:[1,0]
	v_pk_mul_f32 v[88:89], v[88:89], v[230:231] op_sel_hi:[1,0]
	v_pk_mul_f32 v[80:81], v[80:81], v[230:231] op_sel_hi:[1,0]
	v_pk_mul_f32 v[90:91], v[90:91], v[230:231] op_sel_hi:[1,0]
	v_pk_mul_f32 v[82:83], v[82:83], v[230:231] op_sel_hi:[1,0]
	v_mul_f32_e32 v188, 0xbfb8aa3b, v92
	v_mul_f32_e32 v189, 0xbfb8aa3b, v93
	v_mul_f32_e32 v190, 0xbfb8aa3b, v94
	v_mul_f32_e32 v191, 0xbfb8aa3b, v95
	v_mul_f32_e32 v192, 0xbfb8aa3b, v88
	v_mul_f32_e32 v193, 0xbfb8aa3b, v89
	v_mul_f32_e32 v194, 0xbfb8aa3b, v90
	v_mul_f32_e32 v195, 0xbfb8aa3b, v91
	v_pk_mul_f32 v[84:85], v[92:93], v[84:85]
	v_pk_mul_f32 v[86:87], v[94:95], v[86:87]
	v_pk_mul_f32 v[80:81], v[88:89], v[80:81]
	v_pk_mul_f32 v[82:83], v[90:91], v[82:83]
	v_exp_f32_e32 v188, v188
	v_exp_f32_e32 v189, v189
	v_exp_f32_e32 v190, v190
	v_exp_f32_e32 v191, v191
	v_exp_f32_e32 v192, v192
	v_exp_f32_e32 v193, v193
	v_exp_f32_e32 v194, v194
	v_exp_f32_e32 v195, v195
	v_add_f32_e32 v188, 1.0, v188
	v_add_f32_e32 v189, 1.0, v189
	v_add_f32_e32 v190, 1.0, v190
	v_add_f32_e32 v191, 1.0, v191
	v_add_f32_e32 v192, 1.0, v192
	v_add_f32_e32 v193, 1.0, v193
	v_add_f32_e32 v194, 1.0, v194
	v_add_f32_e32 v195, 1.0, v195
	v_rcp_f32_e32 v92, v188
	v_rcp_f32_e32 v93, v189
	v_rcp_f32_e32 v94, v190
	v_rcp_f32_e32 v95, v191
	v_rcp_f32_e32 v88, v192
	v_rcp_f32_e32 v89, v193
	v_rcp_f32_e32 v90, v194
	v_rcp_f32_e32 v91, v195
	v_pk_mul_f32 v[84:85], v[84:85], v[92:93]
	v_pk_mul_f32 v[86:87], v[86:87], v[94:95]
	v_pk_mul_f32 v[80:81], v[80:81], v[88:89]
	v_pk_mul_f32 v[82:83], v[82:83], v[90:91]
	v_cvt_pk_bf16_f32 v92, v84, v85
	v_cvt_pk_bf16_f32 v93, v86, v87
	v_cvt_pk_bf16_f32 v94, v80, v81
	v_cvt_pk_bf16_f32 v95, v82, v83
	global_store_dwordx4 v[146:147], v[92:95], off
	v_lshl_add_u64 v[146:147], v[146:147], 0, s[52:53]
	v_pk_mul_f32 v[76:77], v[76:77], v[232:233] op_sel_hi:[1,0]
	v_pk_mul_f32 v[68:69], v[68:69], v[232:233] op_sel_hi:[1,0]
	v_pk_mul_f32 v[78:79], v[78:79], v[232:233] op_sel_hi:[1,0]
	v_pk_mul_f32 v[70:71], v[70:71], v[232:233] op_sel_hi:[1,0]
	v_pk_mul_f32 v[72:73], v[72:73], v[232:233] op_sel_hi:[1,0]
	v_pk_mul_f32 v[64:65], v[64:65], v[232:233] op_sel_hi:[1,0]
	v_pk_mul_f32 v[74:75], v[74:75], v[232:233] op_sel_hi:[1,0]
	v_pk_mul_f32 v[66:67], v[66:67], v[232:233] op_sel_hi:[1,0]
	v_mul_f32_e32 v188, 0xbfb8aa3b, v76
	v_mul_f32_e32 v189, 0xbfb8aa3b, v77
	v_mul_f32_e32 v190, 0xbfb8aa3b, v78
	v_mul_f32_e32 v191, 0xbfb8aa3b, v79
	v_mul_f32_e32 v192, 0xbfb8aa3b, v72
	v_mul_f32_e32 v193, 0xbfb8aa3b, v73
	v_mul_f32_e32 v194, 0xbfb8aa3b, v74
	v_mul_f32_e32 v195, 0xbfb8aa3b, v75
	v_pk_mul_f32 v[68:69], v[76:77], v[68:69]
	v_pk_mul_f32 v[70:71], v[78:79], v[70:71]
	v_pk_mul_f32 v[64:65], v[72:73], v[64:65]
	v_pk_mul_f32 v[66:67], v[74:75], v[66:67]
	v_exp_f32_e32 v188, v188
	v_exp_f32_e32 v189, v189
	v_exp_f32_e32 v190, v190
	v_exp_f32_e32 v191, v191
	v_exp_f32_e32 v192, v192
	v_exp_f32_e32 v193, v193
	v_exp_f32_e32 v194, v194
	v_exp_f32_e32 v195, v195
	v_add_f32_e32 v188, 1.0, v188
	v_add_f32_e32 v189, 1.0, v189
	v_add_f32_e32 v190, 1.0, v190
	v_add_f32_e32 v191, 1.0, v191
	v_add_f32_e32 v192, 1.0, v192
	v_add_f32_e32 v193, 1.0, v193
	v_add_f32_e32 v194, 1.0, v194
	v_add_f32_e32 v195, 1.0, v195
	v_rcp_f32_e32 v76, v188
	v_rcp_f32_e32 v77, v189
	v_rcp_f32_e32 v78, v190
	v_rcp_f32_e32 v79, v191
	v_rcp_f32_e32 v72, v192
	v_rcp_f32_e32 v73, v193
	v_rcp_f32_e32 v74, v194
	v_rcp_f32_e32 v75, v195
	v_pk_mul_f32 v[68:69], v[68:69], v[76:77]
	v_pk_mul_f32 v[70:71], v[70:71], v[78:79]
	v_pk_mul_f32 v[64:65], v[64:65], v[72:73]
	v_pk_mul_f32 v[66:67], v[66:67], v[74:75]
	v_cvt_pk_bf16_f32 v76, v68, v69
	v_cvt_pk_bf16_f32 v77, v70, v71
	v_cvt_pk_bf16_f32 v78, v64, v65
	v_cvt_pk_bf16_f32 v79, v66, v67
	global_store_dwordx4 v[146:147], v[76:79], off
	v_lshl_add_u64 v[146:147], v[146:147], 0, s[54:55]
	v_pk_mul_f32 v[60:61], v[60:61], v[234:235] op_sel_hi:[1,0]
	v_pk_mul_f32 v[52:53], v[52:53], v[234:235] op_sel_hi:[1,0]
	v_pk_mul_f32 v[62:63], v[62:63], v[234:235] op_sel_hi:[1,0]
	v_pk_mul_f32 v[54:55], v[54:55], v[234:235] op_sel_hi:[1,0]
	v_pk_mul_f32 v[56:57], v[56:57], v[234:235] op_sel_hi:[1,0]
	v_pk_mul_f32 v[48:49], v[48:49], v[234:235] op_sel_hi:[1,0]
	v_pk_mul_f32 v[58:59], v[58:59], v[234:235] op_sel_hi:[1,0]
	v_pk_mul_f32 v[50:51], v[50:51], v[234:235] op_sel_hi:[1,0]
	v_mul_f32_e32 v188, 0xbfb8aa3b, v60
	v_mul_f32_e32 v189, 0xbfb8aa3b, v61
	v_mul_f32_e32 v190, 0xbfb8aa3b, v62
	v_mul_f32_e32 v191, 0xbfb8aa3b, v63
	v_mul_f32_e32 v192, 0xbfb8aa3b, v56
	v_mul_f32_e32 v193, 0xbfb8aa3b, v57
	v_mul_f32_e32 v194, 0xbfb8aa3b, v58
	v_mul_f32_e32 v195, 0xbfb8aa3b, v59
	v_pk_mul_f32 v[52:53], v[60:61], v[52:53]
	v_pk_mul_f32 v[54:55], v[62:63], v[54:55]
	v_pk_mul_f32 v[48:49], v[56:57], v[48:49]
	v_pk_mul_f32 v[50:51], v[58:59], v[50:51]
	v_exp_f32_e32 v188, v188
	v_exp_f32_e32 v189, v189
	v_exp_f32_e32 v190, v190
	v_exp_f32_e32 v191, v191
	v_exp_f32_e32 v192, v192
	v_exp_f32_e32 v193, v193
	v_exp_f32_e32 v194, v194
	v_exp_f32_e32 v195, v195
	v_add_f32_e32 v188, 1.0, v188
	v_add_f32_e32 v189, 1.0, v189
	v_add_f32_e32 v190, 1.0, v190
	v_add_f32_e32 v191, 1.0, v191
	v_add_f32_e32 v192, 1.0, v192
	v_add_f32_e32 v193, 1.0, v193
	v_add_f32_e32 v194, 1.0, v194
	v_add_f32_e32 v195, 1.0, v195
	v_rcp_f32_e32 v60, v188
	v_rcp_f32_e32 v61, v189
	v_rcp_f32_e32 v62, v190
	v_rcp_f32_e32 v63, v191
	v_rcp_f32_e32 v56, v192
	v_rcp_f32_e32 v57, v193
	v_rcp_f32_e32 v58, v194
	v_rcp_f32_e32 v59, v195
	v_pk_mul_f32 v[52:53], v[52:53], v[60:61]
	v_pk_mul_f32 v[54:55], v[54:55], v[62:63]
	v_pk_mul_f32 v[48:49], v[48:49], v[56:57]
	v_pk_mul_f32 v[50:51], v[50:51], v[58:59]
	v_cvt_pk_bf16_f32 v60, v52, v53
	v_cvt_pk_bf16_f32 v61, v54, v55
	v_cvt_pk_bf16_f32 v62, v48, v49
	v_cvt_pk_bf16_f32 v63, v50, v51
	global_store_dwordx4 v[146:147], v[60:63], off
	v_lshl_add_u64 v[146:147], v[146:147], 0, s[52:53]
	v_pk_mul_f32 v[44:45], v[44:45], v[236:237] op_sel_hi:[1,0]
	v_pk_mul_f32 v[36:37], v[36:37], v[236:237] op_sel_hi:[1,0]
	v_pk_mul_f32 v[46:47], v[46:47], v[236:237] op_sel_hi:[1,0]
	v_pk_mul_f32 v[38:39], v[38:39], v[236:237] op_sel_hi:[1,0]
	v_pk_mul_f32 v[40:41], v[40:41], v[236:237] op_sel_hi:[1,0]
	v_pk_mul_f32 v[32:33], v[32:33], v[236:237] op_sel_hi:[1,0]
	v_pk_mul_f32 v[42:43], v[42:43], v[236:237] op_sel_hi:[1,0]
	v_pk_mul_f32 v[34:35], v[34:35], v[236:237] op_sel_hi:[1,0]
	v_mul_f32_e32 v188, 0xbfb8aa3b, v44
	v_mul_f32_e32 v189, 0xbfb8aa3b, v45
	v_mul_f32_e32 v190, 0xbfb8aa3b, v46
	v_mul_f32_e32 v191, 0xbfb8aa3b, v47
	v_mul_f32_e32 v192, 0xbfb8aa3b, v40
	v_mul_f32_e32 v193, 0xbfb8aa3b, v41
	v_mul_f32_e32 v194, 0xbfb8aa3b, v42
	v_mul_f32_e32 v195, 0xbfb8aa3b, v43
	v_pk_mul_f32 v[36:37], v[44:45], v[36:37]
	v_pk_mul_f32 v[38:39], v[46:47], v[38:39]
	v_pk_mul_f32 v[32:33], v[40:41], v[32:33]
	v_pk_mul_f32 v[34:35], v[42:43], v[34:35]
	v_exp_f32_e32 v188, v188
	v_exp_f32_e32 v189, v189
	v_exp_f32_e32 v190, v190
	v_exp_f32_e32 v191, v191
	v_exp_f32_e32 v192, v192
	v_exp_f32_e32 v193, v193
	v_exp_f32_e32 v194, v194
	v_exp_f32_e32 v195, v195
	v_add_f32_e32 v188, 1.0, v188
	v_add_f32_e32 v189, 1.0, v189
	v_add_f32_e32 v190, 1.0, v190
	v_add_f32_e32 v191, 1.0, v191
	v_add_f32_e32 v192, 1.0, v192
	v_add_f32_e32 v193, 1.0, v193
	v_add_f32_e32 v194, 1.0, v194
	v_add_f32_e32 v195, 1.0, v195
	v_rcp_f32_e32 v44, v188
	v_rcp_f32_e32 v45, v189
	v_rcp_f32_e32 v46, v190
	v_rcp_f32_e32 v47, v191
	v_rcp_f32_e32 v40, v192
	v_rcp_f32_e32 v41, v193
	v_rcp_f32_e32 v42, v194
	v_rcp_f32_e32 v43, v195
	v_pk_mul_f32 v[36:37], v[36:37], v[44:45]
	v_pk_mul_f32 v[38:39], v[38:39], v[46:47]
	v_pk_mul_f32 v[32:33], v[32:33], v[40:41]
	v_pk_mul_f32 v[34:35], v[34:35], v[42:43]
	v_cvt_pk_bf16_f32 v44, v36, v37
	v_cvt_pk_bf16_f32 v45, v38, v39
	v_cvt_pk_bf16_f32 v46, v32, v33
	v_cvt_pk_bf16_f32 v47, v34, v35
	global_store_dwordx4 v[146:147], v[44:47], off
	v_lshl_add_u64 v[146:147], v[146:147], 0, s[52:53]
	v_pk_mul_f32 v[28:29], v[28:29], v[238:239] op_sel_hi:[1,0]
	v_pk_mul_f32 v[20:21], v[20:21], v[238:239] op_sel_hi:[1,0]
	v_pk_mul_f32 v[30:31], v[30:31], v[238:239] op_sel_hi:[1,0]
	v_pk_mul_f32 v[22:23], v[22:23], v[238:239] op_sel_hi:[1,0]
	v_pk_mul_f32 v[24:25], v[24:25], v[238:239] op_sel_hi:[1,0]
	v_pk_mul_f32 v[16:17], v[16:17], v[238:239] op_sel_hi:[1,0]
	v_pk_mul_f32 v[26:27], v[26:27], v[238:239] op_sel_hi:[1,0]
	v_pk_mul_f32 v[18:19], v[18:19], v[238:239] op_sel_hi:[1,0]
	v_mul_f32_e32 v188, 0xbfb8aa3b, v28
	v_mul_f32_e32 v189, 0xbfb8aa3b, v29
	v_mul_f32_e32 v190, 0xbfb8aa3b, v30
	v_mul_f32_e32 v191, 0xbfb8aa3b, v31
	v_mul_f32_e32 v192, 0xbfb8aa3b, v24
	v_mul_f32_e32 v193, 0xbfb8aa3b, v25
	v_mul_f32_e32 v194, 0xbfb8aa3b, v26
	v_mul_f32_e32 v195, 0xbfb8aa3b, v27
	v_pk_mul_f32 v[20:21], v[28:29], v[20:21]
	v_pk_mul_f32 v[22:23], v[30:31], v[22:23]
	v_pk_mul_f32 v[16:17], v[24:25], v[16:17]
	v_pk_mul_f32 v[18:19], v[26:27], v[18:19]
	v_exp_f32_e32 v188, v188
	v_exp_f32_e32 v189, v189
	v_exp_f32_e32 v190, v190
	v_exp_f32_e32 v191, v191
	v_exp_f32_e32 v192, v192
	v_exp_f32_e32 v193, v193
	v_exp_f32_e32 v194, v194
	v_exp_f32_e32 v195, v195
	v_add_f32_e32 v188, 1.0, v188
	v_add_f32_e32 v189, 1.0, v189
	v_add_f32_e32 v190, 1.0, v190
	v_add_f32_e32 v191, 1.0, v191
	v_add_f32_e32 v192, 1.0, v192
	v_add_f32_e32 v193, 1.0, v193
	v_add_f32_e32 v194, 1.0, v194
	v_add_f32_e32 v195, 1.0, v195
	v_rcp_f32_e32 v28, v188
	v_rcp_f32_e32 v29, v189
	v_rcp_f32_e32 v30, v190
	v_rcp_f32_e32 v31, v191
	v_rcp_f32_e32 v24, v192
	v_rcp_f32_e32 v25, v193
	v_rcp_f32_e32 v26, v194
	v_rcp_f32_e32 v27, v195
	v_pk_mul_f32 v[20:21], v[20:21], v[28:29]
	v_pk_mul_f32 v[22:23], v[22:23], v[30:31]
	v_pk_mul_f32 v[16:17], v[16:17], v[24:25]
	v_pk_mul_f32 v[18:19], v[18:19], v[26:27]
	v_cvt_pk_bf16_f32 v28, v20, v21
	v_cvt_pk_bf16_f32 v29, v22, v23
	v_cvt_pk_bf16_f32 v30, v16, v17
	v_cvt_pk_bf16_f32 v31, v18, v19
	global_store_dwordx4 v[146:147], v[28:31], off
	v_lshl_add_u64 v[146:147], v[146:147], 0, s[52:53]
	v_pk_mul_f32 v[12:13], v[12:13], v[240:241] op_sel_hi:[1,0]
	v_pk_mul_f32 v[4:5], v[4:5], v[240:241] op_sel_hi:[1,0]
	v_pk_mul_f32 v[14:15], v[14:15], v[240:241] op_sel_hi:[1,0]
	v_pk_mul_f32 v[6:7], v[6:7], v[240:241] op_sel_hi:[1,0]
	v_pk_mul_f32 v[8:9], v[8:9], v[240:241] op_sel_hi:[1,0]
	v_pk_mul_f32 v[0:1], v[0:1], v[240:241] op_sel_hi:[1,0]
	v_pk_mul_f32 v[10:11], v[10:11], v[240:241] op_sel_hi:[1,0]
	v_pk_mul_f32 v[2:3], v[2:3], v[240:241] op_sel_hi:[1,0]
	v_mul_f32_e32 v188, 0xbfb8aa3b, v12
	v_mul_f32_e32 v189, 0xbfb8aa3b, v13
	v_mul_f32_e32 v190, 0xbfb8aa3b, v14
	v_mul_f32_e32 v191, 0xbfb8aa3b, v15
	v_mul_f32_e32 v192, 0xbfb8aa3b, v8
	v_mul_f32_e32 v193, 0xbfb8aa3b, v9
	v_mul_f32_e32 v194, 0xbfb8aa3b, v10
	v_mul_f32_e32 v195, 0xbfb8aa3b, v11
	v_pk_mul_f32 v[4:5], v[12:13], v[4:5]
	v_pk_mul_f32 v[6:7], v[14:15], v[6:7]
	v_pk_mul_f32 v[0:1], v[8:9], v[0:1]
	v_pk_mul_f32 v[2:3], v[10:11], v[2:3]
	v_exp_f32_e32 v188, v188
	v_exp_f32_e32 v189, v189
	v_exp_f32_e32 v190, v190
	v_exp_f32_e32 v191, v191
	v_exp_f32_e32 v192, v192
	v_exp_f32_e32 v193, v193
	v_exp_f32_e32 v194, v194
	v_exp_f32_e32 v195, v195
	v_add_f32_e32 v188, 1.0, v188
	v_add_f32_e32 v189, 1.0, v189
	v_add_f32_e32 v190, 1.0, v190
	v_add_f32_e32 v191, 1.0, v191
	v_add_f32_e32 v192, 1.0, v192
	v_add_f32_e32 v193, 1.0, v193
	v_add_f32_e32 v194, 1.0, v194
	v_add_f32_e32 v195, 1.0, v195
	v_rcp_f32_e32 v12, v188
	v_rcp_f32_e32 v13, v189
	v_rcp_f32_e32 v14, v190
	v_rcp_f32_e32 v15, v191
	v_rcp_f32_e32 v8, v192
	v_rcp_f32_e32 v9, v193
	v_rcp_f32_e32 v10, v194
	v_rcp_f32_e32 v11, v195
	v_pk_mul_f32 v[4:5], v[4:5], v[12:13]
	v_pk_mul_f32 v[6:7], v[6:7], v[14:15]
	v_pk_mul_f32 v[0:1], v[0:1], v[8:9]
	v_pk_mul_f32 v[2:3], v[2:3], v[10:11]
	v_cvt_pk_bf16_f32 v12, v4, v5
	v_cvt_pk_bf16_f32 v13, v6, v7
	v_cvt_pk_bf16_f32 v14, v0, v1
	v_cvt_pk_bf16_f32 v15, v2, v3
	global_store_dwordx4 v[146:147], v[12:15], off
	s_and_b64 vcc, exec, s[2:3]
	s_cbranch_vccz .Lp4_noreduce
	s_waitcnt vmcnt(8)
	v_add_f32_e32 v156, v156, v157
	v_add_f32_e32 v160, v160, v161
	v_add_f32_e32 v164, v164, v165
	v_add_f32_e32 v168, v168, v169
	v_add_f32_e32 v172, v172, v173
	v_add_f32_e32 v176, v176, v177
	v_add_f32_e32 v180, v180, v181
	v_add_f32_e32 v184, v184, v185
	v_add_f32_e32 v158, v158, v159
	v_add_f32_e32 v162, v162, v163
	v_add_f32_e32 v166, v166, v167
	v_add_f32_e32 v170, v170, v171
	v_add_f32_e32 v174, v174, v175
	v_add_f32_e32 v178, v178, v179
	v_add_f32_e32 v182, v182, v183
	v_add_f32_e32 v186, v186, v187
	v_add_f32_e32 v156, v156, v158
	v_add_f32_e32 v160, v160, v162
	v_add_f32_e32 v164, v164, v166
	v_add_f32_e32 v168, v168, v170
	v_add_f32_e32 v172, v172, v174
	v_add_f32_e32 v176, v176, v178
	v_add_f32_e32 v180, v180, v182
	v_add_f32_e32 v184, v184, v186
	v_mov_b32_e32 v157, v156
	v_mov_b32_e32 v161, v160
	v_mov_b32_e32 v165, v164
	v_mov_b32_e32 v169, v168
	v_mov_b32_e32 v173, v172
	v_mov_b32_e32 v177, v176
	v_mov_b32_e32 v181, v180
	v_mov_b32_e32 v185, v184
	v_permlane16_swap_b32_e32 v157, v156
	v_permlane16_swap_b32_e32 v161, v160
	v_permlane16_swap_b32_e32 v165, v164
	v_permlane16_swap_b32_e32 v169, v168
	v_permlane16_swap_b32_e32 v173, v172
	v_permlane16_swap_b32_e32 v177, v176
	v_permlane16_swap_b32_e32 v181, v180
	v_permlane16_swap_b32_e32 v185, v184
	v_add_f32_e32 v156, v156, v157
	v_add_f32_e32 v160, v160, v161
	v_add_f32_e32 v164, v164, v165
	v_add_f32_e32 v168, v168, v169
	v_add_f32_e32 v172, v172, v173
	v_add_f32_e32 v176, v176, v177
	v_add_f32_e32 v180, v180, v181
	v_add_f32_e32 v184, v184, v185
	v_mov_b32_e32 v157, v156
	v_mov_b32_e32 v161, v160
	v_mov_b32_e32 v165, v164
	v_mov_b32_e32 v169, v168
	v_mov_b32_e32 v173, v172
	v_mov_b32_e32 v177, v176
	v_mov_b32_e32 v181, v180
	v_mov_b32_e32 v185, v184
	v_permlane32_swap_b32_e32 v157, v156
	v_permlane32_swap_b32_e32 v161, v160
	v_permlane32_swap_b32_e32 v165, v164
	v_permlane32_swap_b32_e32 v169, v168
	v_permlane32_swap_b32_e32 v173, v172
	v_permlane32_swap_b32_e32 v177, v176
	v_permlane32_swap_b32_e32 v181, v180
	v_permlane32_swap_b32_e32 v185, v184
	v_add_f32_e32 v156, v156, v157
	v_add_f32_e32 v160, v160, v161
	v_add_f32_e32 v164, v164, v165
	v_add_f32_e32 v168, v168, v169
	v_add_f32_e32 v172, v172, v173
	v_add_f32_e32 v176, v176, v177
	v_add_f32_e32 v180, v180, v181
	v_add_f32_e32 v184, v184, v185
	v_fmamk_f32 v156, v156, 0x3a800000, v155
	v_fmamk_f32 v160, v160, 0x3a800000, v155
	v_fmamk_f32 v164, v164, 0x3a800000, v155
	v_fmamk_f32 v168, v168, 0x3a800000, v155
	v_fmamk_f32 v172, v172, 0x3a800000, v155
	v_fmamk_f32 v176, v176, 0x3a800000, v155
	v_fmamk_f32 v180, v180, 0x3a800000, v155
	v_fmamk_f32 v184, v184, 0x3a800000, v155
	v_rsq_f32_e32 v226, v156
	v_rsq_f32_e32 v228, v160
	v_rsq_f32_e32 v230, v164
	v_rsq_f32_e32 v232, v168
	v_rsq_f32_e32 v234, v172
	v_rsq_f32_e32 v236, v176
	v_rsq_f32_e32 v238, v180
	v_rsq_f32_e32 v240, v184
.Lp4_noreduce:
	s_andn2_b64 vcc, exec, s[2:3]
	s_mov_b64 s[2:3], -1
	s_cbranch_vccnz .LBB0_789
	s_andn2_b64 vcc, exec, s[6:7]
	s_cbranch_vccnz .LBB0_788
	s_barrier
	s_branch .LBB0_788
